# g2 step: before the first barrier wait only for the VT write (lgkmcnt 8), operand reads stay in flight across the barrier
# baseline (speedup 1.0000x reference)
.LBB0_135:
	ds_read_b128 v[72:75], v120
	ds_read_b128 v[76:79], v120 offset:64
	ds_read_b128 v[148:151], v121
	ds_read_b128 v[152:155], v121 offset:64
	ds_read_b128 v[80:83], v120 offset:128
	ds_read_b128 v[156:159], v120 offset:192
	ds_read_b128 v[160:163], v121 offset:128
	ds_read_b128 v[164:167], v121 offset:192
	ds_read_b64 v[168:169], v122 offset:62464
	s_setprio 1
	s_waitcnt lgkmcnt(6)
	v_mfma_f32_16x16x32_bf16 v[72:75], v[72:75], v[148:151], 0
	s_waitcnt lgkmcnt(5)
	v_mfma_f32_16x16x32_bf16 v[72:75], v[76:79], v[152:155], v[72:75]
	s_waitcnt lgkmcnt(0)
	v_lshlrev_b32_e32 v76, 16, v168
	v_and_b32_e32 v77, 0xffff0000, v168
	v_lshlrev_b32_e32 v78, 16, v169
	v_mfma_f32_16x16x32_bf16 v[72:75], v[80:83], v[160:163], v[72:75]
	v_and_b32_e32 v79, 0xffff0000, v169
	v_mfma_f32_16x16x32_bf16 v[72:75], v[156:159], v[164:167], v[72:75]
	s_nop 7
	v_pk_add_f32 v[72:73], v[76:77], v[72:73] neg_lo:[0,1] neg_hi:[0,1]
	v_pk_add_f32 v[74:75], v[78:79], v[74:75] neg_lo:[0,1] neg_hi:[0,1]
	v_cvt_pk_bf16_f32 v72, v72, v73
	v_cvt_pk_bf16_f32 v73, v74, v75
	ds_write_b64 v124, v[72:73]
	ds_read_b128 v[72:75], v120 offset:17408
	ds_read_b128 v[156:159], v120 offset:17472
	ds_read_b128 v[168:171], v120 offset:17536
	ds_read_b128 v[172:175], v120 offset:17600
	ds_read_b128 v[190:193], v125 offset:53248
	ds_read_b128 v[194:197], v125 offset:53312
	ds_read_b128 v[80:83], v126 offset:34816
	ds_read_b128 v[76:79], v126 offset:34880
	s_setprio 0
	s_waitcnt lgkmcnt(8)
	s_barrier
	s_setprio 1
	s_waitcnt lgkmcnt(7)
	v_mfma_f32_16x16x32_bf16 v[72:75], v[72:75], v[148:151], 0
	v_add_u32_e32 v149, v123, v119
	s_waitcnt lgkmcnt(6)
	v_mfma_f32_16x16x32_bf16 v[72:75], v[156:159], v[152:155], v[72:75]
	ds_read_b128 v[150:153], v149
	ds_read_b128 v[154:157], v149 offset:64
	ds_read_b128 v[216:219], v147
	ds_read_b128 v[220:223], v147 offset:64
	ds_read_b128 v[224:227], v147 offset:2304
	ds_read_b128 v[228:231], v147 offset:2368
	s_waitcnt lgkmcnt(7)
	v_mfma_f32_16x16x32_bf16 v[72:75], v[168:171], v[160:163], v[72:75]
	s_waitcnt lgkmcnt(6)
	v_mfma_f32_16x16x32_bf16 v[72:75], v[172:175], v[164:167], v[72:75]
	s_waitcnt lgkmcnt(5)
	v_mfma_f32_16x16x32_bf16 v[72:75], v[190:193], v[150:153], v[72:75]
	s_waitcnt lgkmcnt(4)
	v_mfma_f32_16x16x32_bf16 v[72:75], v[194:197], v[154:157], v[72:75]
	s_and_saveexec_b64 s[24:25], s[6:7]
	s_cbranch_execz .LBB0_139
	s_nop 5
	v_cvt_pk_bf16_f32 v72, v72, s0
	global_store_short v[110:111], v72, off offset:-4096
	s_or_b64 exec, exec, s[24:25]
	s_and_saveexec_b64 s[24:25], s[8:9]
	s_cbranch_execnz .LBB0_140

.LBB0_145:
	s_or_b64 exec, exec, s[24:25]
	s_waitcnt lgkmcnt(0)
	s_barrier
	s_add_i32 s24, s45, 1
	s_cmp_ge_u32 s24, s43
	s_cbranch_scc1 .LBB0_133
	s_add_i32 s24, s45, 3
	s_min_u32 s24, s24, s44
	s_add_i32 s24, s24, s42
	s_mul_hi_u32 s25, s24, 0x12100
	s_mul_i32 s24, s24, 0x12100
	s_add_u32 s24, s37, s24
	s_addc_u32 s25, s39, s25
	s_add_u32 s26, s24, 0x8000
	s_addc_u32 s27, s25, 0
	s_add_u32 s46, s24, 0xc000
	v_mov_b32_e32 v99, v137
	v_lshl_add_u64 v[22:23], s[24:25], 0, v[106:107]
	s_addc_u32 s47, s25, 0
	v_lshl_add_u64 v[22:23], v[22:23], 0, v[98:99]
	v_lshl_add_u64 v[0:1], s[24:25], 0, v[102:103]
	v_lshl_add_u64 v[4:5], s[24:25], 0, v[104:105]
	v_lshl_add_u64 v[6:7], s[26:27], 0, v[102:103]
	v_lshl_add_u64 v[12:13], s[26:27], 0, v[104:105]
	v_lshl_add_u64 v[14:15], s[46:47], 0, v[106:107]
	v_lshl_add_u64 v[20:21], v[84:85], 1, s[46:47]
	v_add_co_u32_e32 v24, vcc, s97, v22
	v_lshl_add_u64 v[0:1], v[0:1], 0, v[136:137]
	v_lshl_add_u64 v[4:5], v[4:5], 0, v[136:137]
	v_lshl_add_u64 v[8:9], v[6:7], 0, v[136:137]
	v_lshl_add_u64 v[12:13], v[12:13], 0, v[136:137]
	v_lshl_add_u64 v[16:17], v[14:15], 0, v[98:99]
	v_lshl_add_u64 v[20:21], v[20:21], 0, v[98:99]
	v_addc_co_u32_e32 v25, vcc, 0, v23, vcc
	v_mov_b32_e32 v109, v137
	global_load_dword v148, v206, s[24:25]
	s_nop 0
	global_load_dwordx4 v[0:3], v[0:1], off
	s_nop 0
	global_load_dwordx4 v[4:7], v[4:5], off
	s_nop 0
	global_load_dwordx4 v[8:11], v[8:9], off
	s_nop 0
	global_load_dwordx4 v[12:15], v[12:13], off
	s_nop 0
	global_load_dwordx4 v[16:19], v[16:17], off
	s_nop 0
	global_load_dwordx4 v[20:23], v[20:21], off
	s_nop 0
	global_load_dwordx4 v[28:31], v[24:25], off
	v_lshl_add_u64 v[24:25], s[24:25], 0, v[108:109]
	v_lshl_add_u64 v[24:25], v[24:25], 0, v[98:99]
	v_add_co_u32_e32 v24, vcc, s93, v24
	s_nop 1
	v_addc_co_u32_e32 v25, vcc, 0, v25, vcc
	global_load_dwordx4 v[32:35], v[24:25], off
	ds_read_b128 v[24:27], v135
	ds_read_b128 v[36:39], v135 offset:64
	ds_read_b128 v[150:153], v138
	ds_read_b128 v[154:157], v138 offset:64
	ds_read_b128 v[80:83], v135 offset:128
	ds_read_b128 v[158:161], v135 offset:192
	ds_read_b128 v[162:165], v138 offset:128
	ds_read_b128 v[166:169], v138 offset:192
	ds_read_b64 v[170:171], v139
	s_setprio 1
	s_waitcnt lgkmcnt(6)
	v_mfma_f32_16x16x32_bf16 v[24:27], v[24:27], v[150:153], 0
	s_waitcnt lgkmcnt(5)
	v_mfma_f32_16x16x32_bf16 v[24:27], v[36:39], v[154:157], v[24:27]
	s_waitcnt lgkmcnt(0)
	v_lshlrev_b32_e32 v36, 16, v170
	v_and_b32_e32 v37, 0xffff0000, v170
	v_lshlrev_b32_e32 v38, 16, v171
	v_mfma_f32_16x16x32_bf16 v[24:27], v[80:83], v[162:165], v[24:27]
	v_and_b32_e32 v39, 0xffff0000, v171
	v_mfma_f32_16x16x32_bf16 v[24:27], v[158:161], v[166:169], v[24:27]
	s_nop 7
	v_pk_add_f32 v[24:25], v[36:37], v[24:25] neg_lo:[0,1] neg_hi:[0,1]
	v_pk_add_f32 v[26:27], v[38:39], v[26:27] neg_lo:[0,1] neg_hi:[0,1]
	v_cvt_pk_bf16_f32 v24, v24, v25
	v_cvt_pk_bf16_f32 v25, v26, v27
	ds_write_b64 v124, v[24:25]
	ds_read_b128 v[24:27], v146
	ds_read_b128 v[158:161], v146 offset:64
	ds_read_b128 v[170:173], v146 offset:128
	ds_read_b128 v[174:177], v146 offset:192
	ds_read_b128 v[190:193], v140
	ds_read_b128 v[194:197], v140 offset:64
	ds_read_b128 v[80:83], v141
	ds_read_b128 v[36:39], v141 offset:64
	s_setprio 0
	s_waitcnt lgkmcnt(8)
	s_barrier
	s_setprio 1
	s_waitcnt lgkmcnt(7)
	v_mfma_f32_16x16x32_bf16 v[24:27], v[24:27], v[150:153], 0
	s_waitcnt lgkmcnt(6)
	v_mfma_f32_16x16x32_bf16 v[24:27], v[158:161], v[154:157], v[24:27]
	ds_read_b128 v[150:153], v149
	ds_read_b128 v[154:157], v149 offset:64
	ds_read_b128 v[216:219], v147
	ds_read_b128 v[220:223], v147 offset:64
	ds_read_b128 v[224:227], v147 offset:2304
	ds_read_b128 v[228:231], v147 offset:2368
	s_waitcnt lgkmcnt(7)
	v_mfma_f32_16x16x32_bf16 v[24:27], v[170:173], v[162:165], v[24:27]
	s_waitcnt lgkmcnt(6)
	v_mfma_f32_16x16x32_bf16 v[24:27], v[174:177], v[166:169], v[24:27]
	s_waitcnt lgkmcnt(5)
	v_mfma_f32_16x16x32_bf16 v[24:27], v[190:193], v[150:153], v[24:27]
	s_waitcnt lgkmcnt(4)
	v_mfma_f32_16x16x32_bf16 v[24:27], v[194:197], v[154:157], v[24:27]
	s_and_saveexec_b64 s[24:25], s[6:7]
	s_cbranch_execz .LBB0_150
	s_nop 5
	v_cvt_pk_bf16_f32 v24, v24, s0
	global_store_short v[110:111], v24, off
	s_or_b64 exec, exec, s[24:25]
	s_and_saveexec_b64 s[24:25], s[8:9]
	s_cbranch_execnz .LBB0_151
